# per-workgroup L2 writeback in the grid barriers skipped only when phase 0 has verified (hardware XCC_ID, min/max per group) that the workgroup's whole barrier group runs on one XCD; otherwise the base
# baseline (speedup 1.0000x reference)
; template <int PHI> DI void run_from(const Ctx& c, char* smem, int ph0, int ph1) {
;   const Params& p = c.p; (void)p;
;   if constexpr (PHI < NPHASE) {
;     if (ph0 <= PHI && PHI < ph1) {
;       run_phase<PHI>(c, smem);
;       if (PHI + 1 < ph1) {
;         if constexpr (PHI == 0) { __syncthreads(); cg::this_grid().sync(); }
;         else grid_barrier(c, (unsigned)PHI);
;       }
;     }
;     run_from<PHI + 1>(c, smem, ph0, ph1);
;   }
; }
; __global__ void __launch_bounds__(256, 2) mega(Params p, int ph0, int ph1) {
;   extern __shared__ __attribute__((aligned(16))) char smem[];
;   const Ctx c{p, __builtin_amdgcn_readfirstlane((int)(__builtin_amdgcn_workitem_id_x() >> 6))};
;   run_from<0>(c, smem, ph0, ph1);
; }
_Z4mega6Paramsii:
	s_mov_b32 s96, s2
	s_mov_b64 s[74:75], s[0:1]
	s_load_dwordx4 s[92:95], s[0:1], 0x170
	s_load_dwordx16 s[76:91], s[0:1], 0x0
	s_nop 0
	s_load_dwordx16 s[0:15], s[74:75], 0x40
	v_and_b32_e32 v1, 0x3ff, v0
	s_waitcnt lgkmcnt(0)
	s_cmp_gt_i32 s94, 0
	v_readfirstlane_b32 s72, v1
	v_writelane_b32 v253, s0, 0
	s_nop 1
	v_writelane_b32 v253, s1, 1
	v_writelane_b32 v253, s2, 2
	v_writelane_b32 v253, s3, 3
	v_writelane_b32 v253, s4, 4
	v_writelane_b32 v253, s5, 5
	v_writelane_b32 v253, s6, 6
	v_writelane_b32 v253, s7, 7
	v_writelane_b32 v253, s8, 8
	v_writelane_b32 v253, s9, 9
	v_writelane_b32 v253, s10, 10
	v_writelane_b32 v253, s11, 11
	v_writelane_b32 v253, s12, 12
	v_writelane_b32 v253, s13, 13
	v_writelane_b32 v253, s14, 14
	v_writelane_b32 v253, s15, 15
	s_load_dwordx16 s[0:15], s[74:75], 0xc0
	s_waitcnt lgkmcnt(0)
	v_writelane_b32 v253, s0, 16
	s_nop 1
	v_writelane_b32 v253, s1, 17
	v_writelane_b32 v253, s2, 18
	v_writelane_b32 v253, s3, 19
	v_writelane_b32 v253, s4, 20
	v_writelane_b32 v253, s5, 21
	v_writelane_b32 v253, s6, 22
	v_writelane_b32 v253, s7, 23
	v_writelane_b32 v253, s8, 24
	v_writelane_b32 v253, s9, 25
	v_writelane_b32 v253, s10, 26
	v_writelane_b32 v253, s11, 27
	v_writelane_b32 v253, s12, 28
	v_writelane_b32 v253, s13, 29
	v_writelane_b32 v253, s14, 30
	v_writelane_b32 v253, s15, 31
	s_load_dwordx16 s[0:15], s[74:75], 0x100
	s_waitcnt lgkmcnt(0)
	v_writelane_b32 v253, s0, 32
	s_nop 1
	v_writelane_b32 v253, s1, 33
	v_writelane_b32 v253, s2, 34
	v_writelane_b32 v253, s3, 35
	v_writelane_b32 v253, s4, 36
	v_writelane_b32 v253, s5, 37
	v_writelane_b32 v253, s6, 38
	v_writelane_b32 v253, s7, 39
	v_writelane_b32 v253, s8, 40
	v_writelane_b32 v253, s9, 41
	v_writelane_b32 v253, s10, 42
	v_writelane_b32 v253, s11, 43
	v_writelane_b32 v253, s12, 44
	v_writelane_b32 v253, s13, 45
	v_writelane_b32 v253, s14, 46
	v_writelane_b32 v253, s15, 47
	s_cselect_b64 s[0:1], -1, 0
	s_cmp_lt_i32 s95, 1
	s_cselect_b64 s[2:3], -1, 0
	s_or_b64 s[0:1], s[0:1], s[2:3]
	s_and_b64 vcc, exec, s[0:1]
	s_cbranch_vccnz .LBB0_60
	s_getreg_b32 s98, hwreg(HW_REG_XCC_ID)
	s_and_b32 s98, s98, 15
	s_and_b32 s99, s96, 7
	s_lshl_b32 s99, s99, 3
	s_add_u32 s99, s99, 0x1fe00080
	s_mov_b64 s[100:101], exec
	s_mov_b64 exec, 1
	v_mov_b32_e32 v2, s99
	v_mov_b32_e32 v3, s98
	global_atomic_umin v2, v3, s[92:93]
	s_sub_u32 s98, 15, s98
	v_mov_b32_e32 v3, s98
	global_atomic_umin v2, v3, s[92:93] offset:4
	s_mov_b64 exec, s[100:101]
	s_cmp_eq_u32 s96, 0
	s_cbranch_scc1 .LBB0_6
	v_mbcnt_lo_u32_b32 v2, -1, 0
	v_mbcnt_hi_u32_b32 v22, -1, v2
	s_cbranch_execnz .LBB0_7

; DI void grid_barrier(const Ctx& c, unsigned idx) {
;     ...
;   asm volatile("s_waitcnt vmcnt(0)" ::: "memory");
;   __syncthreads();
;   if (TIDX == 0) {
;     unsigned* bar = (unsigned*)(p.ws + OFF_BAR);
;     const unsigned G = gridDim.x, grp = blockIdx.x & 7u;
;     const unsigned gsz = (G >> 3) + ((grp < (G & 7u)) ? 1u : 0u);
;     const unsigned ngrp = G < 8u ? G : 8u;
;     __builtin_amdgcn_fence(__ATOMIC_RELEASE, "agent");
;     asm volatile("s_waitcnt vmcnt(0)" ::: "memory");
;     const unsigned old = __hip_atomic_fetch_add(bar + 64 * (1 + grp), 1u, __ATOMIC_RELAXED, __HIP_MEMORY_SCOPE_AGENT);
.LBB0_330:
	s_cmp_lt_i32 s95, 3
	s_cbranch_scc1 .LBB0_344
	s_and_b32 s99, s96, 7
	s_lshl_b32 s99, s99, 3
	s_add_u32 s99, s99, 0x1fe00080
	s_load_dwordx2 s[100:101], s[92:93], s99
	s_waitcnt vmcnt(0)
	v_sub_u32_e32 v0, 0, v195
	v_cmp_eq_u32_e32 vcc, s28, v0
	s_barrier
	s_and_saveexec_b64 s[0:1], vcc
	s_cbranch_execz .LBB0_343
	s_add_u32 s6, s92, 0x1fe00000
	s_mov_b64 s[4:5], exec
	s_addc_u32 s7, s93, 0
	s_and_b32 s10, s96, 7
	s_waitcnt lgkmcnt(0)
	s_add_u32 s98, s100, s101
	s_cmp_eq_u32 s98, 15
	s_cbranch_scc1 .Lxg0
	buffer_wbl2 sc1
.Lxg0:
	s_waitcnt vmcnt(0)
	s_waitcnt vmcnt(0)
	s_lshl_b32 s2, s10, 8
	v_mbcnt_lo_u32_b32 v0, s4, 0
	s_add_u32 s2, s6, s2
	v_mbcnt_hi_u32_b32 v0, s5, v0
	s_addc_u32 s3, s7, 0
	v_cmp_eq_u32_e32 vcc, 0, v0
	s_and_saveexec_b64 s[8:9], vcc
	s_cbranch_execz .LBB0_334
	s_bcnt1_i32_b64 s4, s[4:5]
	v_mov_b32_e32 v1, 0
	v_mov_b32_e32 v2, s4
	global_atomic_add v1, v1, v2, s[2:3] offset:256 sc0

; DI void grid_barrier(const Ctx& c, unsigned idx) {
;     ...
;   asm volatile("s_waitcnt vmcnt(0)" ::: "memory");
;   __syncthreads();
;   if (TIDX == 0) {
;     unsigned* bar = (unsigned*)(p.ws + OFF_BAR);
;     const unsigned G = gridDim.x, grp = blockIdx.x & 7u;
;     const unsigned gsz = (G >> 3) + ((grp < (G & 7u)) ? 1u : 0u);
;     const unsigned ngrp = G < 8u ? G : 8u;
;     __builtin_amdgcn_fence(__ATOMIC_RELEASE, "agent");
;     asm volatile("s_waitcnt vmcnt(0)" ::: "memory");
;     const unsigned old = __hip_atomic_fetch_add(bar + 64 * (1 + grp), 1u, __ATOMIC_RELAXED, __HIP_MEMORY_SCOPE_AGENT);
.LBB0_535:
	s_or_b64 exec, exec, s[0:1]
	s_cmp_lt_i32 s95, 4
	s_cbranch_scc1 .LBB0_549
	s_and_b32 s99, s96, 7
	s_lshl_b32 s99, s99, 3
	s_add_u32 s99, s99, 0x1fe00080
	s_load_dwordx2 s[100:101], s[92:93], s99
	s_waitcnt vmcnt(0)
	v_sub_u32_e32 v0, 0, v76
	v_cmp_eq_u32_e32 vcc, s21, v0
	s_barrier
	s_and_saveexec_b64 s[0:1], vcc
	s_cbranch_execz .LBB0_548
	s_add_u32 s6, s92, 0x1fe00000
	s_mov_b64 s[4:5], exec
	s_addc_u32 s7, s93, 0
	s_and_b32 s10, s96, 7
	s_waitcnt lgkmcnt(0)
	s_add_u32 s98, s100, s101
	s_cmp_eq_u32 s98, 15
	s_cbranch_scc1 .Lxg1
	buffer_wbl2 sc1

; DI void grid_barrier(const Ctx& c, unsigned idx) {
;     ...
;   asm volatile("s_waitcnt vmcnt(0)" ::: "memory");
;   __syncthreads();
;   if (TIDX == 0) {
;     unsigned* bar = (unsigned*)(p.ws + OFF_BAR);
;     const unsigned G = gridDim.x, grp = blockIdx.x & 7u;
;     const unsigned gsz = (G >> 3) + ((grp < (G & 7u)) ? 1u : 0u);
;     const unsigned ngrp = G < 8u ? G : 8u;
;     __builtin_amdgcn_fence(__ATOMIC_RELEASE, "agent");
;     asm volatile("s_waitcnt vmcnt(0)" ::: "memory");
;     const unsigned old = __hip_atomic_fetch_add(bar + 64 * (1 + grp), 1u, __ATOMIC_RELAXED, __HIP_MEMORY_SCOPE_AGENT);
.LBB0_586:
	s_cmp_lt_u32 s95, 5
	s_cbranch_scc1 .LBB0_600
	s_and_b32 s99, s96, 7
	s_lshl_b32 s99, s99, 3
	s_add_u32 s99, s99, 0x1fe00080
	s_load_dwordx2 s[100:101], s[92:93], s99
	s_waitcnt vmcnt(0)
	v_sub_u32_e32 v0, 0, v136
	v_cmp_eq_u32_e32 vcc, s14, v0
	s_waitcnt lgkmcnt(0)
	s_barrier
	s_and_saveexec_b64 s[0:1], vcc
	s_cbranch_execz .LBB0_599
	s_add_u32 s6, s92, 0x1fe00000
	s_mov_b64 s[4:5], exec
	s_addc_u32 s7, s93, 0
	s_and_b32 s10, s96, 7
	s_waitcnt lgkmcnt(0)
	s_add_u32 s98, s100, s101
	s_cmp_eq_u32 s98, 15
	s_cbranch_scc1 .Lxg2
	buffer_wbl2 sc1

; DI void grid_barrier(const Ctx& c, unsigned idx) {
;     ...
;   asm volatile("s_waitcnt vmcnt(0)" ::: "memory");
;   __syncthreads();
;   if (TIDX == 0) {
;     unsigned* bar = (unsigned*)(p.ws + OFF_BAR);
;     const unsigned G = gridDim.x, grp = blockIdx.x & 7u;
;     const unsigned gsz = (G >> 3) + ((grp < (G & 7u)) ? 1u : 0u);
;     const unsigned ngrp = G < 8u ? G : 8u;
;     __builtin_amdgcn_fence(__ATOMIC_RELEASE, "agent");
;     asm volatile("s_waitcnt vmcnt(0)" ::: "memory");
;     const unsigned old = __hip_atomic_fetch_add(bar + 64 * (1 + grp), 1u, __ATOMIC_RELAXED, __HIP_MEMORY_SCOPE_AGENT);
.LBB0_813:
	s_waitcnt lgkmcnt(0)
	s_cmp_lt_i32 s95, 6
	s_cbranch_scc1 .LBB0_827
	s_and_b32 s99, s96, 7
	s_lshl_b32 s99, s99, 3
	s_add_u32 s99, s99, 0x1fe00080
	s_load_dwordx2 s[100:101], s[92:93], s99
	s_waitcnt vmcnt(0)
	v_mbcnt_hi_u32_b32 v0, -1, v194
	s_and_b32 s0, s72, 0xffffffc0
	v_sub_u32_e32 v0, 0, v0
	v_cmp_eq_u32_e32 vcc, s0, v0
	s_barrier
	s_and_saveexec_b64 s[0:1], vcc
	s_cbranch_execz .LBB0_826
	s_add_u32 s6, s92, 0x1fe00000
	s_mov_b64 s[4:5], exec
	s_addc_u32 s7, s93, 0
	s_and_b32 s10, s96, 7
	s_waitcnt lgkmcnt(0)
	s_add_u32 s98, s100, s101
	s_cmp_eq_u32 s98, 15
	s_cbranch_scc1 .Lxg3
	buffer_wbl2 sc1

; DI void grid_barrier(const Ctx& c, unsigned idx) {
;     ...
;   asm volatile("s_waitcnt vmcnt(0)" ::: "memory");
;   __syncthreads();
;   if (TIDX == 0) {
;     unsigned* bar = (unsigned*)(p.ws + OFF_BAR);
;     const unsigned G = gridDim.x, grp = blockIdx.x & 7u;
;     const unsigned gsz = (G >> 3) + ((grp < (G & 7u)) ? 1u : 0u);
;     const unsigned ngrp = G < 8u ? G : 8u;
;     __builtin_amdgcn_fence(__ATOMIC_RELEASE, "agent");
;     asm volatile("s_waitcnt vmcnt(0)" ::: "memory");
;     const unsigned old = __hip_atomic_fetch_add(bar + 64 * (1 + grp), 1u, __ATOMIC_RELAXED, __HIP_MEMORY_SCOPE_AGENT);
.LBB0_841:
	s_or_b64 exec, exec, s[0:1]
	s_cmp_lt_i32 s95, 7
	s_cbranch_scc1 .LBB0_855
	s_and_b32 s99, s96, 7
	s_lshl_b32 s99, s99, 3
	s_add_u32 s99, s99, 0x1fe00080
	s_load_dwordx2 s[100:101], s[92:93], s99
	s_waitcnt vmcnt(0)
	v_sub_u32_e32 v0, 0, v81
	v_cmp_eq_u32_e32 vcc, s11, v0
	s_waitcnt lgkmcnt(0)
	s_barrier
	s_and_saveexec_b64 s[0:1], vcc
	s_cbranch_execz .LBB0_854
	s_add_u32 s6, s92, 0x1fe00000
	s_mov_b64 s[4:5], exec
	s_addc_u32 s7, s93, 0
	s_and_b32 s10, s96, 7
	s_waitcnt lgkmcnt(0)
	s_add_u32 s98, s100, s101
	s_cmp_eq_u32 s98, 15
	s_cbranch_scc1 .Lxg4
	buffer_wbl2 sc1

; DI void grid_barrier(const Ctx& c, unsigned idx) {
;     ...
;   asm volatile("s_waitcnt vmcnt(0)" ::: "memory");
;   __syncthreads();
;   if (TIDX == 0) {
;     unsigned* bar = (unsigned*)(p.ws + OFF_BAR);
;     const unsigned G = gridDim.x, grp = blockIdx.x & 7u;
;     const unsigned gsz = (G >> 3) + ((grp < (G & 7u)) ? 1u : 0u);
;     const unsigned ngrp = G < 8u ? G : 8u;
;     __builtin_amdgcn_fence(__ATOMIC_RELEASE, "agent");
;     asm volatile("s_waitcnt vmcnt(0)" ::: "memory");
;     const unsigned old = __hip_atomic_fetch_add(bar + 64 * (1 + grp), 1u, __ATOMIC_RELAXED, __HIP_MEMORY_SCOPE_AGENT);
.LBB0_869:
	s_cmp_lt_i32 s95, 8
	s_cbranch_scc1 .LBB0_883
	s_and_b32 s99, s96, 7
	s_lshl_b32 s99, s99, 3
	s_add_u32 s99, s99, 0x1fe00080
	s_load_dwordx2 s[100:101], s[92:93], s99
	s_waitcnt vmcnt(0)
	v_sub_u32_e32 v0, 0, v195
	v_cmp_eq_u32_e32 vcc, s8, v0
	s_barrier
	s_and_saveexec_b64 s[0:1], vcc
	s_cbranch_execz .LBB0_882
	s_add_u32 s6, s92, 0x1fe00000
	s_mov_b64 s[4:5], exec
	s_addc_u32 s7, s93, 0
	s_and_b32 s11, s96, 7
	s_waitcnt lgkmcnt(0)
	s_add_u32 s98, s100, s101
	s_cmp_eq_u32 s98, 15
	s_cbranch_scc1 .Lxg5
	buffer_wbl2 sc1
.Lxg5:
	s_waitcnt vmcnt(0)
	s_waitcnt vmcnt(0)
	s_lshl_b32 s2, s11, 8
	v_mbcnt_lo_u32_b32 v0, s4, 0
	s_add_u32 s2, s6, s2
	v_mbcnt_hi_u32_b32 v0, s5, v0
	s_addc_u32 s3, s7, 0
	v_cmp_eq_u32_e32 vcc, 0, v0
	s_and_saveexec_b64 s[8:9], vcc
	s_cbranch_execz .LBB0_873
	s_bcnt1_i32_b64 s4, s[4:5]
	v_mov_b32_e32 v1, 0
	v_mov_b32_e32 v2, s4
	global_atomic_add v1, v1, v2, s[2:3] offset:256 sc0

; DI void grid_barrier(const Ctx& c, unsigned idx) {
;     ...
;   asm volatile("s_waitcnt vmcnt(0)" ::: "memory");
;   __syncthreads();
;   if (TIDX == 0) {
;     unsigned* bar = (unsigned*)(p.ws + OFF_BAR);
;     const unsigned G = gridDim.x, grp = blockIdx.x & 7u;
;     const unsigned gsz = (G >> 3) + ((grp < (G & 7u)) ? 1u : 0u);
;     const unsigned ngrp = G < 8u ? G : 8u;
;     __builtin_amdgcn_fence(__ATOMIC_RELEASE, "agent");
;     asm volatile("s_waitcnt vmcnt(0)" ::: "memory");
;     const unsigned old = __hip_atomic_fetch_add(bar + 64 * (1 + grp), 1u, __ATOMIC_RELAXED, __HIP_MEMORY_SCOPE_AGENT);
.LBB0_887:
	s_cmp_lt_u32 s95, 9
	s_cbranch_scc1 .LBB0_901
	s_and_b32 s99, s96, 7
	s_lshl_b32 s99, s99, 3
	s_add_u32 s99, s99, 0x1fe00080
	s_load_dwordx2 s[100:101], s[92:93], s99
	s_waitcnt vmcnt(0)
	s_and_b32 s0, s72, 0xffffffc0
	v_sub_u32_e32 v0, 0, v35
	v_cmp_eq_u32_e32 vcc, s0, v0
	s_waitcnt lgkmcnt(0)
	s_barrier
	s_and_saveexec_b64 s[0:1], vcc
	s_cbranch_execz .LBB0_900
	s_add_u32 s4, s92, 0x1fe00000
	s_load_dword s12, s[74:75], 0x180
	s_mov_b64 s[6:7], exec
	s_addc_u32 s5, s93, 0
	s_and_b32 s10, s96, 7
	s_waitcnt lgkmcnt(0)
	s_add_u32 s98, s100, s101
	s_cmp_eq_u32 s98, 15
	s_cbranch_scc1 .Lxg6
	buffer_wbl2 sc1
.Lxg6:
	s_waitcnt vmcnt(0) lgkmcnt(0)
	s_waitcnt vmcnt(0)
	s_lshl_b32 s2, s10, 8
	v_mbcnt_lo_u32_b32 v0, s6, 0
	s_add_u32 s2, s4, s2
	v_mbcnt_hi_u32_b32 v0, s7, v0
	s_addc_u32 s3, s5, 0
	v_cmp_eq_u32_e32 vcc, 0, v0
	s_and_saveexec_b64 s[8:9], vcc
	s_cbranch_execz .LBB0_891
	s_bcnt1_i32_b64 s6, s[6:7]
	v_mov_b32_e32 v1, 0
	v_mov_b32_e32 v2, s6
	global_atomic_add v1, v1, v2, s[2:3] offset:256 sc0

; DI void grid_barrier(const Ctx& c, unsigned idx) {
;     ...
;   asm volatile("s_waitcnt vmcnt(0)" ::: "memory");
;   __syncthreads();
;   if (TIDX == 0) {
;     unsigned* bar = (unsigned*)(p.ws + OFF_BAR);
;     const unsigned G = gridDim.x, grp = blockIdx.x & 7u;
;     const unsigned gsz = (G >> 3) + ((grp < (G & 7u)) ? 1u : 0u);
;     const unsigned ngrp = G < 8u ? G : 8u;
;     __builtin_amdgcn_fence(__ATOMIC_RELEASE, "agent");
;     asm volatile("s_waitcnt vmcnt(0)" ::: "memory");
;     const unsigned old = __hip_atomic_fetch_add(bar + 64 * (1 + grp), 1u, __ATOMIC_RELAXED, __HIP_MEMORY_SCOPE_AGENT);
.LBB0_915:
	s_cmp_lt_i32 s95, 10
	s_cbranch_scc1 .LBB0_929
	s_and_b32 s99, s96, 7
	s_lshl_b32 s99, s99, 3
	s_add_u32 s99, s99, 0x1fe00080
	s_load_dwordx2 s[100:101], s[92:93], s99
	s_waitcnt vmcnt(0)
	v_sub_u32_e32 v0, 0, v195
	v_cmp_eq_u32_e32 vcc, s16, v0
	s_barrier
	s_and_saveexec_b64 s[0:1], vcc
	s_cbranch_execz .LBB0_928
	s_add_u32 s6, s92, 0x1fe00000
	s_mov_b64 s[4:5], exec
	s_addc_u32 s7, s93, 0
	s_and_b32 s10, s96, 7
	s_waitcnt lgkmcnt(0)
	s_add_u32 s98, s100, s101
	s_cmp_eq_u32 s98, 15
	s_cbranch_scc1 .Lxg7
	buffer_wbl2 sc1

; DI void grid_barrier(const Ctx& c, unsigned idx) {
;     ...
;   asm volatile("s_waitcnt vmcnt(0)" ::: "memory");
;   __syncthreads();
;   if (TIDX == 0) {
;     unsigned* bar = (unsigned*)(p.ws + OFF_BAR);
;     const unsigned G = gridDim.x, grp = blockIdx.x & 7u;
;     const unsigned gsz = (G >> 3) + ((grp < (G & 7u)) ? 1u : 0u);
;     const unsigned ngrp = G < 8u ? G : 8u;
;     __builtin_amdgcn_fence(__ATOMIC_RELEASE, "agent");
;     asm volatile("s_waitcnt vmcnt(0)" ::: "memory");
;     const unsigned old = __hip_atomic_fetch_add(bar + 64 * (1 + grp), 1u, __ATOMIC_RELAXED, __HIP_MEMORY_SCOPE_AGENT);
.LBB0_943:
	s_cmp_lt_i32 s95, 11
	s_cbranch_scc1 .LBB0_957
	s_and_b32 s99, s96, 7
	s_lshl_b32 s99, s99, 3
	s_add_u32 s99, s99, 0x1fe00080
	s_load_dwordx2 s[100:101], s[92:93], s99
	s_waitcnt vmcnt(0)
	v_sub_u32_e32 v0, 0, v195
	v_cmp_eq_u32_e32 vcc, s14, v0
	s_barrier
	s_and_saveexec_b64 s[0:1], vcc
	s_cbranch_execz .LBB0_956
	s_add_u32 s6, s92, 0x1fe00000
	s_mov_b64 s[4:5], exec
	s_addc_u32 s7, s93, 0
	s_and_b32 s10, s96, 7
	s_waitcnt lgkmcnt(0)
	s_add_u32 s98, s100, s101
	s_cmp_eq_u32 s98, 15
	s_cbranch_scc1 .Lxg8
	buffer_wbl2 sc1

; DI void grid_barrier(const Ctx& c, unsigned idx) {
;     ...
;   asm volatile("s_waitcnt vmcnt(0)" ::: "memory");
;   __syncthreads();
;   if (TIDX == 0) {
;     unsigned* bar = (unsigned*)(p.ws + OFF_BAR);
;     const unsigned G = gridDim.x, grp = blockIdx.x & 7u;
;     const unsigned gsz = (G >> 3) + ((grp < (G & 7u)) ? 1u : 0u);
;     const unsigned ngrp = G < 8u ? G : 8u;
;     __builtin_amdgcn_fence(__ATOMIC_RELEASE, "agent");
;     asm volatile("s_waitcnt vmcnt(0)" ::: "memory");
;     const unsigned old = __hip_atomic_fetch_add(bar + 64 * (1 + grp), 1u, __ATOMIC_RELAXED, __HIP_MEMORY_SCOPE_AGENT);
.LBB0_961:
	s_cmp_lt_u32 s95, 12
	s_cbranch_scc1 .LBB0_975
	s_and_b32 s99, s96, 7
	s_lshl_b32 s99, s99, 3
	s_add_u32 s99, s99, 0x1fe00080
	s_load_dwordx2 s[100:101], s[92:93], s99
	s_waitcnt vmcnt(0)
	s_and_b32 s0, s72, 0xffffffc0
	v_sub_u32_e32 v0, 0, v35
	v_cmp_eq_u32_e32 vcc, s0, v0
	s_waitcnt lgkmcnt(0)
	s_barrier
	s_and_saveexec_b64 s[0:1], vcc
	s_cbranch_execz .LBB0_974
	s_add_u32 s4, s92, 0x1fe00000
	s_load_dword s12, s[74:75], 0x180
	s_mov_b64 s[6:7], exec
	s_addc_u32 s5, s93, 0
	s_and_b32 s10, s96, 7
	s_waitcnt lgkmcnt(0)
	s_add_u32 s98, s100, s101
	s_cmp_eq_u32 s98, 15
	s_cbranch_scc1 .Lxg9
	buffer_wbl2 sc1

; DI void grid_barrier(const Ctx& c, unsigned idx) {
;     ...
;   asm volatile("s_waitcnt vmcnt(0)" ::: "memory");
;   __syncthreads();
;   if (TIDX == 0) {
;     unsigned* bar = (unsigned*)(p.ws + OFF_BAR);
;     const unsigned G = gridDim.x, grp = blockIdx.x & 7u;
;     const unsigned gsz = (G >> 3) + ((grp < (G & 7u)) ? 1u : 0u);
;     const unsigned ngrp = G < 8u ? G : 8u;
;     __builtin_amdgcn_fence(__ATOMIC_RELEASE, "agent");
;     asm volatile("s_waitcnt vmcnt(0)" ::: "memory");
;     const unsigned old = __hip_atomic_fetch_add(bar + 64 * (1 + grp), 1u, __ATOMIC_RELAXED, __HIP_MEMORY_SCOPE_AGENT);
.LBB0_1245:
	s_cmp_lt_i32 s95, 13
	s_cbranch_scc1 .LBB0_1259
	s_and_b32 s99, s96, 7
	s_lshl_b32 s99, s99, 3
	s_add_u32 s99, s99, 0x1fe00080
	s_load_dwordx2 s[100:101], s[92:93], s99
	s_waitcnt vmcnt(0)
	v_sub_u32_e32 v0, 0, v195
	v_cmp_eq_u32_e32 vcc, s36, v0
	s_barrier
	s_and_saveexec_b64 s[0:1], vcc
	s_cbranch_execz .LBB0_1258
	s_add_u32 s6, s92, 0x1fe00000
	s_mov_b64 s[4:5], exec
	s_addc_u32 s7, s93, 0
	s_and_b32 s10, s96, 7
	s_waitcnt lgkmcnt(0)
	s_add_u32 s98, s100, s101
	s_cmp_eq_u32 s98, 15
	s_cbranch_scc1 .Lxg10
	buffer_wbl2 sc1

; DI void grid_barrier(const Ctx& c, unsigned idx) {
;     ...
;   asm volatile("s_waitcnt vmcnt(0)" ::: "memory");
;   __syncthreads();
;   if (TIDX == 0) {
;     unsigned* bar = (unsigned*)(p.ws + OFF_BAR);
;     const unsigned G = gridDim.x, grp = blockIdx.x & 7u;
;     const unsigned gsz = (G >> 3) + ((grp < (G & 7u)) ? 1u : 0u);
;     const unsigned ngrp = G < 8u ? G : 8u;
;     __builtin_amdgcn_fence(__ATOMIC_RELEASE, "agent");
;     asm volatile("s_waitcnt vmcnt(0)" ::: "memory");
;     const unsigned old = __hip_atomic_fetch_add(bar + 64 * (1 + grp), 1u, __ATOMIC_RELAXED, __HIP_MEMORY_SCOPE_AGENT);
.LBB0_1710:
	s_cmp_lt_i32 s95, 14
	s_cbranch_scc1 .LBB0_1724
	s_and_b32 s99, s96, 7
	s_lshl_b32 s99, s99, 3
	s_add_u32 s99, s99, 0x1fe00080
	s_load_dwordx2 s[100:101], s[92:93], s99
	s_waitcnt vmcnt(0)
	v_mbcnt_hi_u32_b32 v0, -1, v194
	s_and_b32 s0, s72, 0xffffffc0
	v_sub_u32_e32 v0, 0, v0
	v_cmp_eq_u32_e32 vcc, s0, v0
	s_barrier
	s_and_saveexec_b64 s[0:1], vcc
	s_cbranch_execz .LBB0_1723
	s_add_u32 s6, s92, 0x1fe00000
	s_mov_b64 s[4:5], exec
	s_addc_u32 s7, s93, 0
	s_and_b32 s10, s96, 7
	s_waitcnt lgkmcnt(0)
	s_add_u32 s98, s100, s101
	s_cmp_eq_u32 s98, 15
	s_cbranch_scc1 .Lxg11
	buffer_wbl2 sc1

; DI void grid_barrier(const Ctx& c, unsigned idx) {
;     ...
;   asm volatile("s_waitcnt vmcnt(0)" ::: "memory");
;   __syncthreads();
;   if (TIDX == 0) {
;     unsigned* bar = (unsigned*)(p.ws + OFF_BAR);
;     const unsigned G = gridDim.x, grp = blockIdx.x & 7u;
;     const unsigned gsz = (G >> 3) + ((grp < (G & 7u)) ? 1u : 0u);
;     const unsigned ngrp = G < 8u ? G : 8u;
;     __builtin_amdgcn_fence(__ATOMIC_RELEASE, "agent");
;     asm volatile("s_waitcnt vmcnt(0)" ::: "memory");
;     const unsigned old = __hip_atomic_fetch_add(bar + 64 * (1 + grp), 1u, __ATOMIC_RELAXED, __HIP_MEMORY_SCOPE_AGENT);
.LBB0_1802:
	s_or_b64 exec, exec, s[0:1]
	s_cmp_lt_i32 s95, 15
	s_cbranch_scc1 .LBB0_1816
	s_and_b32 s99, s96, 7
	s_lshl_b32 s99, s99, 3
	s_add_u32 s99, s99, 0x1fe00080
	s_load_dwordx2 s[100:101], s[92:93], s99
	s_waitcnt vmcnt(0)
	v_sub_u32_e32 v0, 0, v81
	v_cmp_eq_u32_e32 vcc, s16, v0
	s_waitcnt lgkmcnt(0)
	s_barrier
	s_and_saveexec_b64 s[0:1], vcc
	s_cbranch_execz .LBB0_1815
	s_add_u32 s6, s92, 0x1fe00000
	s_mov_b64 s[4:5], exec
	s_addc_u32 s7, s93, 0
	s_and_b32 s10, s96, 7
	s_waitcnt lgkmcnt(0)
	s_add_u32 s98, s100, s101
	s_cmp_eq_u32 s98, 15
	s_cbranch_scc1 .Lxg12
	buffer_wbl2 sc1

; DI void grid_barrier(const Ctx& c, unsigned idx) {
;     ...
;   asm volatile("s_waitcnt vmcnt(0)" ::: "memory");
;   __syncthreads();
;   if (TIDX == 0) {
;     unsigned* bar = (unsigned*)(p.ws + OFF_BAR);
;     const unsigned G = gridDim.x, grp = blockIdx.x & 7u;
;     const unsigned gsz = (G >> 3) + ((grp < (G & 7u)) ? 1u : 0u);
;     const unsigned ngrp = G < 8u ? G : 8u;
;     __builtin_amdgcn_fence(__ATOMIC_RELEASE, "agent");
;     asm volatile("s_waitcnt vmcnt(0)" ::: "memory");
;     const unsigned old = __hip_atomic_fetch_add(bar + 64 * (1 + grp), 1u, __ATOMIC_RELAXED, __HIP_MEMORY_SCOPE_AGENT);
.LBB0_1830:
	s_cmp_lt_i32 s95, 16
	s_cbranch_scc1 .LBB0_1844
	s_and_b32 s99, s96, 7
	s_lshl_b32 s99, s99, 3
	s_add_u32 s99, s99, 0x1fe00080
	s_load_dwordx2 s[100:101], s[92:93], s99
	s_waitcnt vmcnt(0)
	v_sub_u32_e32 v0, 0, v195
	v_cmp_eq_u32_e32 vcc, s16, v0
	s_barrier
	s_and_saveexec_b64 s[0:1], vcc
	s_cbranch_execz .LBB0_1843
	s_add_u32 s6, s92, 0x1fe00000
	s_mov_b64 s[4:5], exec
	s_addc_u32 s7, s93, 0
	s_and_b32 s10, s96, 7
	s_waitcnt lgkmcnt(0)
	s_add_u32 s98, s100, s101
	s_cmp_eq_u32 s98, 15
	s_cbranch_scc1 .Lxg13
	buffer_wbl2 sc1

; DI void grid_barrier(const Ctx& c, unsigned idx) {
;     ...
;   asm volatile("s_waitcnt vmcnt(0)" ::: "memory");
;   __syncthreads();
;   if (TIDX == 0) {
;     unsigned* bar = (unsigned*)(p.ws + OFF_BAR);
;     const unsigned G = gridDim.x, grp = blockIdx.x & 7u;
;     const unsigned gsz = (G >> 3) + ((grp < (G & 7u)) ? 1u : 0u);
;     const unsigned ngrp = G < 8u ? G : 8u;
;     __builtin_amdgcn_fence(__ATOMIC_RELEASE, "agent");
;     asm volatile("s_waitcnt vmcnt(0)" ::: "memory");
;     const unsigned old = __hip_atomic_fetch_add(bar + 64 * (1 + grp), 1u, __ATOMIC_RELAXED, __HIP_MEMORY_SCOPE_AGENT);
.LBB0_1858:
	s_cmp_lt_i32 s95, 17
	s_cbranch_scc1 .LBB0_1872
	s_and_b32 s99, s96, 7
	s_lshl_b32 s99, s99, 3
	s_add_u32 s99, s99, 0x1fe00080
	s_load_dwordx2 s[100:101], s[92:93], s99
	s_waitcnt vmcnt(0)
	v_sub_u32_e32 v0, 0, v195
	v_cmp_eq_u32_e32 vcc, s8, v0
	s_barrier
	s_and_saveexec_b64 s[0:1], vcc
	s_cbranch_execz .LBB0_1871
	s_add_u32 s6, s92, 0x1fe00000
	s_mov_b64 s[4:5], exec
	s_addc_u32 s7, s93, 0
	s_and_b32 s11, s96, 7
	s_waitcnt lgkmcnt(0)
	s_add_u32 s98, s100, s101
	s_cmp_eq_u32 s98, 15
	s_cbranch_scc1 .Lxg14
	buffer_wbl2 sc1

; DI void grid_barrier(const Ctx& c, unsigned idx) {
;     ...
;   asm volatile("s_waitcnt vmcnt(0)" ::: "memory");
;   __syncthreads();
;   if (TIDX == 0) {
;     unsigned* bar = (unsigned*)(p.ws + OFF_BAR);
;     const unsigned G = gridDim.x, grp = blockIdx.x & 7u;
;     const unsigned gsz = (G >> 3) + ((grp < (G & 7u)) ? 1u : 0u);
;     const unsigned ngrp = G < 8u ? G : 8u;
;     __builtin_amdgcn_fence(__ATOMIC_RELEASE, "agent");
;     asm volatile("s_waitcnt vmcnt(0)" ::: "memory");
;     const unsigned old = __hip_atomic_fetch_add(bar + 64 * (1 + grp), 1u, __ATOMIC_RELAXED, __HIP_MEMORY_SCOPE_AGENT);
.LBB0_1876:
	s_cmp_lt_u32 s95, 18
	s_cbranch_scc1 .LBB0_1890
	s_and_b32 s99, s96, 7
	s_lshl_b32 s99, s99, 3
	s_add_u32 s99, s99, 0x1fe00080
	s_load_dwordx2 s[100:101], s[92:93], s99
	s_waitcnt vmcnt(0)
	s_and_b32 s0, s72, 0xffffffc0
	v_sub_u32_e32 v0, 0, v35
	v_cmp_eq_u32_e32 vcc, s0, v0
	s_waitcnt lgkmcnt(0)
	s_barrier
	s_and_saveexec_b64 s[0:1], vcc
	s_cbranch_execz .LBB0_1889
	s_add_u32 s4, s92, 0x1fe00000
	s_load_dword s12, s[74:75], 0x180
	s_mov_b64 s[6:7], exec
	s_addc_u32 s5, s93, 0
	s_and_b32 s10, s96, 7
	s_waitcnt lgkmcnt(0)
	s_add_u32 s98, s100, s101
	s_cmp_eq_u32 s98, 15
	s_cbranch_scc1 .Lxg15
	buffer_wbl2 sc1

; DI void grid_barrier(const Ctx& c, unsigned idx) {
;     ...
;   asm volatile("s_waitcnt vmcnt(0)" ::: "memory");
;   __syncthreads();
;   if (TIDX == 0) {
;     unsigned* bar = (unsigned*)(p.ws + OFF_BAR);
;     const unsigned G = gridDim.x, grp = blockIdx.x & 7u;
;     const unsigned gsz = (G >> 3) + ((grp < (G & 7u)) ? 1u : 0u);
;     const unsigned ngrp = G < 8u ? G : 8u;
;     __builtin_amdgcn_fence(__ATOMIC_RELEASE, "agent");
;     asm volatile("s_waitcnt vmcnt(0)" ::: "memory");
;     const unsigned old = __hip_atomic_fetch_add(bar + 64 * (1 + grp), 1u, __ATOMIC_RELAXED, __HIP_MEMORY_SCOPE_AGENT);
.LBB0_1904:
	s_cmp_lt_i32 s95, 19
	s_cbranch_scc1 .LBB0_1918
	s_and_b32 s99, s96, 7
	s_lshl_b32 s99, s99, 3
	s_add_u32 s99, s99, 0x1fe00080
	s_load_dwordx2 s[100:101], s[92:93], s99
	s_waitcnt vmcnt(0)
	v_sub_u32_e32 v0, 0, v195
	v_cmp_eq_u32_e32 vcc, s16, v0
	s_barrier
	s_and_saveexec_b64 s[0:1], vcc
	s_cbranch_execz .LBB0_1917
	s_add_u32 s6, s92, 0x1fe00000
	s_mov_b64 s[4:5], exec
	s_addc_u32 s7, s93, 0
	s_and_b32 s10, s96, 7
	s_waitcnt lgkmcnt(0)
	s_add_u32 s98, s100, s101
	s_cmp_eq_u32 s98, 15
	s_cbranch_scc1 .Lxg16
	buffer_wbl2 sc1

; DI void grid_barrier(const Ctx& c, unsigned idx) {
;     ...
;   asm volatile("s_waitcnt vmcnt(0)" ::: "memory");
;   __syncthreads();
;   if (TIDX == 0) {
;     unsigned* bar = (unsigned*)(p.ws + OFF_BAR);
;     const unsigned G = gridDim.x, grp = blockIdx.x & 7u;
;     const unsigned gsz = (G >> 3) + ((grp < (G & 7u)) ? 1u : 0u);
;     const unsigned ngrp = G < 8u ? G : 8u;
;     __builtin_amdgcn_fence(__ATOMIC_RELEASE, "agent");
;     asm volatile("s_waitcnt vmcnt(0)" ::: "memory");
;     const unsigned old = __hip_atomic_fetch_add(bar + 64 * (1 + grp), 1u, __ATOMIC_RELAXED, __HIP_MEMORY_SCOPE_AGENT);
.LBB0_1932:
	s_cmp_lt_i32 s95, 20
	s_cbranch_scc1 .LBB0_1946
	s_and_b32 s99, s96, 7
	s_lshl_b32 s99, s99, 3
	s_add_u32 s99, s99, 0x1fe00080
	s_load_dwordx2 s[100:101], s[92:93], s99
	s_waitcnt vmcnt(0)
	v_sub_u32_e32 v0, 0, v195
	v_cmp_eq_u32_e32 vcc, s14, v0
	s_barrier
	s_and_saveexec_b64 s[0:1], vcc
	s_cbranch_execz .LBB0_1945
	s_add_u32 s6, s92, 0x1fe00000
	s_mov_b64 s[4:5], exec
	s_addc_u32 s7, s93, 0
	s_and_b32 s10, s96, 7
	s_waitcnt lgkmcnt(0)
	s_add_u32 s98, s100, s101
	s_cmp_eq_u32 s98, 15
	s_cbranch_scc1 .Lxg17
	buffer_wbl2 sc1

; DI void grid_barrier(const Ctx& c, unsigned idx) {
;     ...
;   asm volatile("s_waitcnt vmcnt(0)" ::: "memory");
;   __syncthreads();
;   if (TIDX == 0) {
;     unsigned* bar = (unsigned*)(p.ws + OFF_BAR);
;     const unsigned G = gridDim.x, grp = blockIdx.x & 7u;
;     const unsigned gsz = (G >> 3) + ((grp < (G & 7u)) ? 1u : 0u);
;     const unsigned ngrp = G < 8u ? G : 8u;
;     __builtin_amdgcn_fence(__ATOMIC_RELEASE, "agent");
;     asm volatile("s_waitcnt vmcnt(0)" ::: "memory");
;     const unsigned old = __hip_atomic_fetch_add(bar + 64 * (1 + grp), 1u, __ATOMIC_RELAXED, __HIP_MEMORY_SCOPE_AGENT);
.LBB0_1950:
	s_cmp_lt_u32 s95, 21
	s_cbranch_scc1 .LBB0_1964
	s_and_b32 s99, s96, 7
	s_lshl_b32 s99, s99, 3
	s_add_u32 s99, s99, 0x1fe00080
	s_load_dwordx2 s[100:101], s[92:93], s99
	s_waitcnt vmcnt(0)
	s_and_b32 s0, s72, 0xffffffc0
	v_sub_u32_e32 v0, 0, v21
	v_cmp_eq_u32_e32 vcc, s0, v0
	s_waitcnt lgkmcnt(0)
	s_barrier
	s_and_saveexec_b64 s[0:1], vcc
	s_cbranch_execz .LBB0_1963
	s_add_u32 s4, s92, 0x1fe00000
	s_load_dword s12, s[74:75], 0x180
	s_mov_b64 s[6:7], exec
	s_addc_u32 s5, s93, 0
	s_and_b32 s10, s96, 7
	s_waitcnt lgkmcnt(0)
	s_add_u32 s98, s100, s101
	s_cmp_eq_u32 s98, 15
	s_cbranch_scc1 .Lxg18
	buffer_wbl2 sc1
